# rs_prologue of the k0/k4 GEMM phases: load-only pre-pass puts all row tiles' partial-sum loads in flight before the serialized table loop (prologue de-serialisation)
# speedup vs baseline: 1.0124x; 1.0124x over previous
.Lrsp0_loop:
	v_cmp_gt_i64_e32 vcc, s[28:29], v[222:223]
	s_cbranch_vccnz .Lrsp0_done
	s_ashr_i32 s7, s28, 31
	s_lshr_b32 s7, s7, 29
	s_add_i32 s7, s28, s7
	s_ashr_i32 s8, s7, 3
	s_and_b32 s7, s7, -8
	s_sub_i32 s7, s28, s7
	s_cmp_lt_i32 s7, 0
	s_movk_i32 s9, 0x161
	s_cselect_b32 s9, s9, 0x160
	s_mul_i32 s7, s7, s9
	s_add_i32 s7, s7, s8
	s_mul_hi_i32 s8, s7, 0x2e8ba2e9
	s_lshr_b32 s9, s8, 31
	s_ashr_i32 s8, s8, 5
	s_add_i32 s8, s8, s9
	s_lshl_b32 s34, s8, 3
	s_sub_i32 s9, 0x80, s34
	s_min_i32 s9, s9, 8
	s_abs_i32 s9, s9
	v_cvt_f32_u32_e32 v5, s9
	s_sub_i32 s10, 0, s9
	s_mulk_i32 s8, 0xb0
	s_sub_i32 s7, s7, s8
	v_rcp_iflag_f32_e32 v5, v5
	s_ashr_i32 s8, s7, 31
	s_abs_i32 s7, s7
	v_mul_f32_e32 v5, 0x4f7ffffe, v5
	v_cvt_u32_f32_e32 v5, v5
	s_nop 0
	v_readfirstlane_b32 s11, v5
	s_mul_i32 s10, s10, s11
	s_mul_hi_u32 s10, s11, s10
	s_add_i32 s11, s11, s10
	s_mul_hi_u32 s10, s7, s11
	s_mul_i32 s10, s10, s9
	s_sub_i32 s7, s7, s10
	s_sub_i32 s10, s7, s9
	s_cmp_ge_u32 s7, s9
	s_cselect_b32 s7, s10, s7
	s_sub_i32 s10, s7, s9
	s_cmp_ge_u32 s7, s9
	s_cselect_b32 s7, s10, s7
	s_xor_b32 s7, s7, s8
	s_sub_i32 s7, s7, s8
	s_add_i32 s34, s34, s7
	v_readlane_b32 s7, v251, 30
	s_sub_i32 s7, s34, s7
	s_cmp_lt_u32 s7, 24
	s_cbranch_scc0 .Lrsp0_next
	s_lshl_b32 s31, 1, s7
	s_and_b32 s8, s31, s5
	s_cmp_lg_u32 s8, 0
	s_cbranch_scc1 .Lrsp0_next
	v_lshl_add_u32 v6, s34, 8, v1
	v_ashrrev_i32_e32 v7, 31, v6
	v_lshlrev_b64 v[6:7], 6, v[6:7]
	v_lshl_add_u64 v[10:11], v[2:3], 0, v[6:7]
	global_load_dwordx4 v[200:203], v[10:11], off
	global_load_dwordx4 v[204:207], v[10:11], off offset:16
	s_or_b32 s5, s31, s5
.Lrsp0_next:
	s_add_u32 s28, s28, s4
	s_addc_u32 s29, s29, s6
	s_branch .Lrsp0_loop
.Lrsp0_done:
	s_mov_b64 s[28:29], s[2:3]
	s_mov_b32 s5, 0
	s_branch .LBB0_35

.LBB0_40:
	v_readlane_b32 s5, v251, 30
	s_waitcnt vmcnt(0) lgkmcnt(0)
	s_barrier

.Lrsp1_loop:
	v_cmp_gt_i64_e32 vcc, s[28:29], v[226:227]
	s_cbranch_vccnz .Lrsp1_done
	s_ashr_i32 s7, s28, 31
	s_lshr_b32 s7, s7, 29
	s_add_i32 s7, s28, s7
	s_ashr_i32 s8, s7, 3
	s_and_b32 s7, s7, -8
	s_sub_i32 s7, s28, s7
	s_cmp_lt_i32 s7, 0
	s_movk_i32 s9, 0xc1
	s_cselect_b32 s9, s9, 0xc0
	s_mul_i32 s7, s7, s9
	s_add_i32 s7, s7, s8
	s_mul_hi_i32 s8, s7, 0x2aaaaaab
	s_lshr_b32 s9, s8, 31
	s_ashr_i32 s8, s8, 4
	s_add_i32 s8, s8, s9
	s_lshl_b32 s40, s8, 3
	s_sub_i32 s9, 0x80, s40
	s_min_i32 s9, s9, 8
	s_abs_i32 s9, s9
	v_cvt_f32_u32_e32 v5, s9
	s_sub_i32 s10, 0, s9
	s_mulk_i32 s8, 0x60
	s_sub_i32 s7, s7, s8
	v_rcp_iflag_f32_e32 v5, v5
	s_ashr_i32 s8, s7, 31
	s_abs_i32 s7, s7
	v_mul_f32_e32 v5, 0x4f7ffffe, v5
	v_cvt_u32_f32_e32 v5, v5
	s_nop 0
	v_readfirstlane_b32 s11, v5
	s_mul_i32 s10, s10, s11
	s_mul_hi_u32 s10, s11, s10
	s_add_i32 s11, s11, s10
	s_mul_hi_u32 s10, s7, s11
	s_mul_i32 s10, s10, s9
	s_sub_i32 s7, s7, s10
	s_sub_i32 s10, s7, s9
	s_cmp_ge_u32 s7, s9
	s_cselect_b32 s7, s10, s7
	s_sub_i32 s10, s7, s9
	s_cmp_ge_u32 s7, s9
	s_cselect_b32 s7, s10, s7
	s_xor_b32 s7, s7, s8
	s_sub_i32 s7, s7, s8
	s_add_i32 s40, s40, s7
	v_readlane_b32 s7, v251, 31
	s_sub_i32 s7, s40, s7
	s_cmp_lt_u32 s7, 24
	s_cbranch_scc0 .Lrsp1_next
	s_lshl_b32 s34, 1, s7
	s_and_b32 s8, s34, s5
	s_cmp_lg_u32 s8, 0
	s_cbranch_scc1 .Lrsp1_next
	v_lshl_add_u32 v6, s40, 8, v1
	v_ashrrev_i32_e32 v7, 31, v6
	v_lshlrev_b64 v[6:7], 6, v[6:7]
	v_lshl_add_u64 v[10:11], v[2:3], 0, v[6:7]
	global_load_dwordx4 v[200:203], v[10:11], off
	global_load_dwordx4 v[204:207], v[10:11], off offset:16
	s_or_b32 s5, s34, s5

.LBB0_487:
	v_readlane_b32 s5, v251, 31
	s_waitcnt vmcnt(0) lgkmcnt(0)
	s_barrier
